# v32 + counted lgkmcnt waits before MLA QK groups 3-6 (each group waits only for its own fragments)
# baseline (speedup 1.0000x reference)
.LBB0_2904:
	v_add_u32_e32 v0, s28, v183
	ds_read_b128 v[2:5], v0 offset:24576
	ds_read_b128 v[6:9], v0 offset:28672
	ds_read_b128 v[10:13], v0 offset:32768
	ds_read_b128 v[184:187], v0 offset:36864
	v_exp_f32_e32 v14, v96
	v_exp_f32_e32 v190, v97
	v_exp_f32_e32 v98, v98
	v_exp_f32_e32 v192, v99
	v_exp_f32_e32 v15, v100
	v_exp_f32_e32 v191, v101
	v_exp_f32_e32 v99, v102
	v_exp_f32_e32 v193, v103
	v_add_u32_e32 v0, s28, v182
	v_pk_add_f32 v[96:97], v[14:15], v[190:191]
	v_pk_add_f32 v[100:101], v[98:99], v[192:193]
	s_nop 0
	v_pk_add_f32 v[96:97], v[96:97], v[100:101]
	v_cvt_pk_bf16_f32 v99, v99, v193
	v_pk_add_f32 v[202:203], v[96:97], v[96:97] op_sel_hi:[0,1]
	v_cvt_pk_bf16_f32 v96, v14, v190
	v_cvt_pk_bf16_f32 v97, v98, v192
	v_cvt_pk_bf16_f32 v98, v15, v191
	ds_read_b128 v[100:103], v0 offset:24576
	ds_read_b128 v[190:193], v0 offset:28672
	ds_read_b128 v[194:197], v0 offset:32768
	ds_read_b128 v[198:201], v0 offset:36864
	s_waitcnt lgkmcnt(0)
	v_mfma_f32_32x32x16_bf16 v[64:79], v[2:5], v[96:99], v[64:79]
	v_mfma_f32_32x32x16_bf16 v[48:63], v[6:9], v[96:99], v[48:63]
	v_mfma_f32_32x32x16_bf16 v[32:47], v[10:13], v[96:99], v[32:47]
	v_mfma_f32_32x32x16_bf16 v[16:31], v[184:187], v[96:99], v[16:31]
	v_exp_f32_e32 v2, v104
	v_exp_f32_e32 v4, v105
	v_exp_f32_e32 v3, v106
	v_exp_f32_e32 v5, v107
	v_exp_f32_e32 v6, v108
	v_exp_f32_e32 v8, v109
	v_exp_f32_e32 v7, v110
	v_exp_f32_e32 v9, v111
	v_pk_add_f32 v[10:11], v[2:3], v[4:5]
	v_add_u32_e32 v0, s28, v180
	v_pk_add_f32 v[14:15], v[10:11], v[10:11] op_sel_hi:[0,1]
	v_pk_add_f32 v[10:11], v[6:7], v[8:9]
	v_cvt_pk_bf16_f32 v2, v2, v4
	v_pk_add_f32 v[184:185], v[10:11], v[10:11] op_sel_hi:[0,1]
	v_cvt_pk_bf16_f32 v3, v3, v5
	v_cvt_pk_bf16_f32 v4, v6, v8
	v_cvt_pk_bf16_f32 v5, v7, v9
	ds_read_b128 v[6:9], v0 offset:24576
	ds_read_b128 v[10:13], v0 offset:28672
	ds_read_b128 v[96:99], v0 offset:32768
	ds_read_b128 v[104:107], v0 offset:36864
	v_mfma_f32_32x32x16_bf16 v[64:79], v[100:103], v[2:5], v[64:79]
	v_mfma_f32_32x32x16_bf16 v[48:63], v[190:193], v[2:5], v[48:63]
	v_mfma_f32_32x32x16_bf16 v[32:47], v[194:197], v[2:5], v[32:47]
	v_mfma_f32_32x32x16_bf16 v[16:31], v[198:201], v[2:5], v[16:31]
	v_exp_f32_e32 v0, v80
	v_exp_f32_e32 v2, v81
	v_exp_f32_e32 v3, v82
	v_exp_f32_e32 v4, v83
	v_exp_f32_e32 v5, v84
	v_exp_f32_e32 v14, v85
	v_exp_f32_e32 v80, v86
	v_exp_f32_e32 v81, v87
	v_add_f32_e32 v187, v0, v2
	v_cvt_pk_bf16_f32 v2, v0, v2
	v_add_u32_e32 v0, s28, v175
	v_add_f32_e32 v191, v3, v4
	v_add_f32_e32 v193, v5, v14
	v_add_f32_e32 v195, v80, v81
	v_cvt_pk_bf16_f32 v3, v3, v4
	v_cvt_pk_bf16_f32 v4, v5, v14
	v_cvt_pk_bf16_f32 v5, v80, v81
	ds_read_b128 v[80:83], v0 offset:24576
	ds_read_b128 v[84:87], v0 offset:28672
	ds_read_b128 v[100:103], v0 offset:32768
	ds_read_b128 v[108:111], v0 offset:36864
	s_waitcnt lgkmcnt(0)
	v_mfma_f32_32x32x16_bf16 v[64:79], v[6:9], v[2:5], v[64:79]
	v_mfma_f32_32x32x16_bf16 v[48:63], v[10:13], v[2:5], v[48:63]
	v_mfma_f32_32x32x16_bf16 v[32:47], v[96:99], v[2:5], v[32:47]
	v_mfma_f32_32x32x16_bf16 v[16:31], v[104:107], v[2:5], v[16:31]
	v_exp_f32_e32 v186, v88
	v_exp_f32_e32 v190, v89
	v_exp_f32_e32 v192, v90
	v_exp_f32_e32 v194, v91
	v_exp_f32_e32 v14, v92
	v_exp_f32_e32 v184, v93
	v_exp_f32_e32 v202, v94
	v_exp_f32_e32 v0, v95
	v_cvt_pk_bf16_f32 v2, v186, v190
	v_cvt_pk_bf16_f32 v3, v192, v194
	v_cvt_pk_bf16_f32 v4, v14, v184
	v_cvt_pk_bf16_f32 v5, v202, v0
	s_nop 1
	v_mfma_f32_32x32x16_bf16 v[64:79], v[80:83], v[2:5], v[64:79]
	v_add_f32_e64 v6, v186, v190
	v_add_f32_e64 v7, v187, v191
	v_add_f32_e64 v8, v192, v194
	v_add_f32_e64 v9, v193, v195
	v_add_f32_e64 v10, v202, v0
	v_add_f32_e64 v11, v203, v1
	v_pk_add_f32 v[6:7], v[6:7], v[8:9]
	v_pk_add_f32 v[8:9], v[14:15], v[184:185]
	s_nop 0
	v_pk_add_f32 v[8:9], v[8:9], v[10:11]
	v_mfma_f32_32x32x16_bf16 v[48:63], v[84:87], v[2:5], v[48:63]
	v_add_f32_e64 v6, v6, v8
	v_add_f32_e64 v7, v7, v9
	v_pk_add_f32 v[6:7], v[6:7], v[6:7] op_sel:[0,1] op_sel_hi:[1,0]
	v_mfma_f32_32x32x16_bf16 v[32:47], v[100:103], v[2:5], v[32:47]
	v_mfma_f32_32x32x16_bf16 v[16:31], v[108:111], v[2:5], v[16:31]
	v_mov_b32_e32 v0, v6
	s_nop 1
	v_permlane32_swap_b32_e32 v6, v0
	v_add_f32_e32 v0, v6, v0
	v_add_f32_e32 v171, v171, v0
	v_add_u32_e32 v0, s1, v174
	v_add_u32_e32 v14, s1, v173
	v_add_u32_e32 v15, s1, v170
	ds_read_b128 v[2:5], v0
	ds_read_b128 v[6:9], v0 offset:12288
	ds_read_b128 v[10:13], v14
	ds_read_b128 v[184:187], v14 offset:12288
	v_add_u32_e32 v206, s1, v172
	ds_read_b128 v[190:193], v15
	ds_read_b128 v[194:197], v15 offset:12288
	ds_read_b128 v[198:201], v206
	ds_read_b128 v[202:205], v206 offset:12288
	v_xor_b32_e32 v80, 0x80000000, v181
	v_mov_b32_e32 v81, v80
	v_mov_b32_e32 v82, v80
	v_mov_b32_e32 v83, v80
	v_mov_b32_e32 v84, v80
	v_mov_b32_e32 v85, v80
	v_mov_b32_e32 v86, v80
	v_mov_b32_e32 v87, v80
	v_mov_b32_e32 v88, v80
	v_mov_b32_e32 v89, v80
	v_mov_b32_e32 v90, v80
	v_mov_b32_e32 v91, v80
	v_mov_b32_e32 v92, v80
	v_mov_b32_e32 v93, v80
	v_mov_b32_e32 v94, v80
	v_mov_b32_e32 v95, v80
	s_waitcnt lgkmcnt(0)
	s_nop 0
	v_mfma_f32_32x32x16_bf16 v[96:111], v[2:5], v[112:115], v[80:95]
	v_mfma_f32_32x32x16_bf16 v[80:95], v[6:9], v[112:115], v[80:95]
	v_mfma_f32_32x32x16_bf16 v[96:111], v[10:13], v[116:119], v[96:111]
	v_mfma_f32_32x32x16_bf16 v[80:95], v[184:187], v[116:119], v[80:95]
	ds_read_b128 v[2:5], v14 offset:12416
	ds_read_b128 v[6:9], v14 offset:128
	ds_read_b128 v[10:13], v0 offset:12416
	ds_read_b128 v[184:187], v0 offset:128
	v_mfma_f32_32x32x16_bf16 v[96:111], v[190:193], v[120:123], v[96:111]
	v_mfma_f32_32x32x16_bf16 v[96:111], v[198:201], v[124:127], v[96:111]
	v_mfma_f32_32x32x16_bf16 v[80:95], v[194:197], v[120:123], v[80:95]
	v_mfma_f32_32x32x16_bf16 v[80:95], v[202:205], v[124:127], v[80:95]
	ds_read_b128 v[190:193], v15 offset:128
	ds_read_b128 v[194:197], v15 offset:12416
	ds_read_b128 v[198:201], v206 offset:128
	ds_read_b128 v[202:205], v206 offset:12416
	s_waitcnt lgkmcnt(4)
	v_mfma_f32_32x32x16_bf16 v[96:111], v[184:187], v[128:131], v[96:111]
	v_mfma_f32_32x32x16_bf16 v[96:111], v[6:9], v[132:135], v[96:111]
	v_mfma_f32_32x32x16_bf16 v[80:95], v[10:13], v[128:131], v[80:95]
	v_mfma_f32_32x32x16_bf16 v[80:95], v[2:5], v[132:135], v[80:95]
	ds_read_b128 v[2:5], v14 offset:12544
	ds_read_b128 v[6:9], v14 offset:256
	ds_read_b128 v[10:13], v0 offset:12544
	ds_read_b128 v[184:187], v0 offset:256
	s_waitcnt lgkmcnt(4)
	v_mfma_f32_32x32x16_bf16 v[96:111], v[190:193], v[136:139], v[96:111]
	v_mfma_f32_32x32x16_bf16 v[96:111], v[198:201], v[140:143], v[96:111]
	v_mfma_f32_32x32x16_bf16 v[80:95], v[194:197], v[136:139], v[80:95]
	v_mfma_f32_32x32x16_bf16 v[80:95], v[202:205], v[140:143], v[80:95]
	ds_read_b128 v[190:193], v15 offset:256
	ds_read_b128 v[194:197], v15 offset:12544
	ds_read_b128 v[198:201], v206 offset:256
	ds_read_b128 v[202:205], v206 offset:12544
	s_waitcnt lgkmcnt(4)
	v_mfma_f32_32x32x16_bf16 v[96:111], v[184:187], v[144:147], v[96:111]
	v_mfma_f32_32x32x16_bf16 v[96:111], v[6:9], v[148:151], v[96:111]
	v_mfma_f32_32x32x16_bf16 v[80:95], v[10:13], v[144:147], v[80:95]
	v_mfma_f32_32x32x16_bf16 v[80:95], v[2:5], v[148:151], v[80:95]
	s_waitcnt lgkmcnt(0)
	v_mfma_f32_32x32x16_bf16 v[96:111], v[190:193], v[152:155], v[96:111]
	v_mfma_f32_32x32x16_bf16 v[96:111], v[198:201], v[156:159], v[96:111]
	v_mfma_f32_32x32x16_bf16 v[80:95], v[194:197], v[152:155], v[80:95]
	s_nop 10
	v_max_f32_e32 v0, v97, v97
	v_max_f32_e32 v2, v96, v96
	v_max_f32_e32 v0, v2, v0
	v_max3_f32 v0, v0, v98, v99
	v_max3_f32 v0, v0, v100, v101
	v_max3_f32 v0, v0, v102, v103
	v_max3_f32 v0, v0, v104, v105
	v_mfma_f32_32x32x16_bf16 v[80:95], v[202:205], v[156:159], v[80:95]
	v_max3_f32 v0, v0, v106, v107
	v_max3_f32 v0, v0, v108, v109
	v_max3_f32 v0, v0, v110, v111
	s_mov_b32 s28, 0x41000000
	s_nop 7
	v_max3_f32 v0, v0, v80, v81
	v_max3_f32 v0, v0, v82, v83
	v_max3_f32 v0, v0, v84, v85
	v_max3_f32 v0, v0, v86, v87
	v_max3_f32 v0, v0, v88, v89
	v_max3_f32 v0, v0, v90, v91
	v_max3_f32 v0, v0, v92, v93
	v_max3_f32 v0, v0, v94, v95
	v_mov_b32_e32 v2, v0
	s_nop 1
	v_permlane32_swap_b32_e32 v0, v2
	v_max_f32_e32 v2, v2, v2
	v_max_f32_e32 v0, v0, v0
	v_max_f32_e32 v0, v0, v2
	v_cmp_ge_f32_e32 vcc, s28, v0
	s_cmp_eq_u64 vcc, exec
	s_cbranch_scc1 .LBB0_2906
	v_max_f32_e32 v0, v0, v0
	v_max_f32_e32 v2, 0, v0
	v_exp_f32_e64 v0, -v2
	v_add_f32_e32 v181, v181, v2
	v_sub_f32_e32 v111, v111, v2
	v_sub_f32_e32 v110, v110, v2
	v_pk_mul_f32 v[78:79], v[78:79], v[0:1] op_sel_hi:[1,0]
	v_pk_mul_f32 v[76:77], v[76:77], v[0:1] op_sel_hi:[1,0]
	v_pk_mul_f32 v[74:75], v[74:75], v[0:1] op_sel_hi:[1,0]
	v_pk_mul_f32 v[72:73], v[72:73], v[0:1] op_sel_hi:[1,0]
	v_pk_mul_f32 v[70:71], v[70:71], v[0:1] op_sel_hi:[1,0]
	v_pk_mul_f32 v[68:69], v[68:69], v[0:1] op_sel_hi:[1,0]
	v_pk_mul_f32 v[66:67], v[66:67], v[0:1] op_sel_hi:[1,0]
	v_pk_mul_f32 v[64:65], v[64:65], v[0:1] op_sel_hi:[1,0]
	v_pk_mul_f32 v[62:63], v[62:63], v[0:1] op_sel_hi:[1,0]
	v_pk_mul_f32 v[60:61], v[60:61], v[0:1] op_sel_hi:[1,0]
	v_pk_mul_f32 v[58:59], v[58:59], v[0:1] op_sel_hi:[1,0]
	v_pk_mul_f32 v[56:57], v[56:57], v[0:1] op_sel_hi:[1,0]
	v_pk_mul_f32 v[54:55], v[54:55], v[0:1] op_sel_hi:[1,0]
	v_pk_mul_f32 v[52:53], v[52:53], v[0:1] op_sel_hi:[1,0]
	v_pk_mul_f32 v[50:51], v[50:51], v[0:1] op_sel_hi:[1,0]
	v_pk_mul_f32 v[48:49], v[48:49], v[0:1] op_sel_hi:[1,0]
	v_pk_mul_f32 v[46:47], v[46:47], v[0:1] op_sel_hi:[1,0]
	v_pk_mul_f32 v[44:45], v[44:45], v[0:1] op_sel_hi:[1,0]
	v_pk_mul_f32 v[42:43], v[42:43], v[0:1] op_sel_hi:[1,0]
	v_pk_mul_f32 v[40:41], v[40:41], v[0:1] op_sel_hi:[1,0]
	v_pk_mul_f32 v[38:39], v[38:39], v[0:1] op_sel_hi:[1,0]
	v_pk_mul_f32 v[36:37], v[36:37], v[0:1] op_sel_hi:[1,0]
	v_pk_mul_f32 v[34:35], v[34:35], v[0:1] op_sel_hi:[1,0]
	v_pk_mul_f32 v[32:33], v[32:33], v[0:1] op_sel_hi:[1,0]
	v_pk_mul_f32 v[30:31], v[30:31], v[0:1] op_sel_hi:[1,0]
	v_pk_mul_f32 v[28:29], v[28:29], v[0:1] op_sel_hi:[1,0]
	v_pk_mul_f32 v[26:27], v[26:27], v[0:1] op_sel_hi:[1,0]
	v_pk_mul_f32 v[24:25], v[24:25], v[0:1] op_sel_hi:[1,0]
	v_pk_mul_f32 v[22:23], v[22:23], v[0:1] op_sel_hi:[1,0]
	v_pk_mul_f32 v[20:21], v[20:21], v[0:1] op_sel_hi:[1,0]
	v_pk_mul_f32 v[18:19], v[18:19], v[0:1] op_sel_hi:[1,0]
	v_pk_mul_f32 v[16:17], v[16:17], v[0:1] op_sel_hi:[1,0]
	v_sub_f32_e32 v109, v109, v2
	v_sub_f32_e32 v108, v108, v2
	v_sub_f32_e32 v107, v107, v2
	v_sub_f32_e32 v106, v106, v2
	v_sub_f32_e32 v105, v105, v2
	v_sub_f32_e32 v104, v104, v2
	v_sub_f32_e32 v103, v103, v2
	v_sub_f32_e32 v102, v102, v2
	v_sub_f32_e32 v101, v101, v2
	v_sub_f32_e32 v100, v100, v2
	v_sub_f32_e32 v99, v99, v2
	v_sub_f32_e32 v98, v98, v2
	v_sub_f32_e32 v97, v97, v2
	v_sub_f32_e32 v96, v96, v2
	v_sub_f32_e32 v95, v95, v2
	v_sub_f32_e32 v94, v94, v2
	v_sub_f32_e32 v93, v93, v2
	v_sub_f32_e32 v92, v92, v2
	v_sub_f32_e32 v91, v91, v2
	v_sub_f32_e32 v90, v90, v2
	v_sub_f32_e32 v89, v89, v2
	v_sub_f32_e32 v88, v88, v2
	v_sub_f32_e32 v87, v87, v2
	v_sub_f32_e32 v86, v86, v2
	v_sub_f32_e32 v85, v85, v2
	v_sub_f32_e32 v84, v84, v2
	v_sub_f32_e32 v83, v83, v2
	v_sub_f32_e32 v82, v82, v2
	v_sub_f32_e32 v81, v81, v2
	v_sub_f32_e32 v80, v80, v2
	v_mul_f32_e32 v171, v171, v0
